# grid barrier: non-leader workgroups poll the top-level generation word directly instead of waiting for their XCD leader to republish it (one hop less per barrier)
# speedup vs baseline: 1.0029x; 1.0029x over previous
.LBB0_1170:
	s_or_b64 exec, exec, s[4:5]
	v_cvt_f32_u32_e32 v4, v2
	s_waitcnt vmcnt(0)
	v_readfirstlane_b32 s4, v3
	v_sub_u32_e32 v3, 0, v2
	v_rcp_iflag_f32_e32 v4, v4
	v_add_u32_e32 v5, s4, v1
	v_mul_f32_e32 v4, 0x4f7ffffe, v4
	v_cvt_u32_f32_e32 v4, v4
	v_mul_lo_u32 v1, v3, v4
	v_mul_hi_u32 v1, v4, v1
	v_add_u32_e32 v1, v4, v1
	v_mul_hi_u32 v1, v5, v1
	v_mul_lo_u32 v3, v1, v2
	v_sub_u32_e32 v3, v5, v3
	v_add_u32_e32 v4, 1, v1
	v_cmp_ge_u32_e32 vcc, v3, v2
	s_nop 1
	v_cndmask_b32_e32 v1, v1, v4, vcc
	v_sub_u32_e32 v4, v3, v2
	v_cndmask_b32_e32 v3, v3, v4, vcc
	v_add_u32_e32 v4, 1, v1
	v_cmp_ge_u32_e32 vcc, v3, v2
	v_add_u32_e32 v3, 1, v5
	s_nop 0
	v_cndmask_b32_e32 v1, v1, v4, vcc
	v_mul_lo_u32 v4, v2, v1
	v_add_u32_e32 v2, v4, v2
	v_cmp_ne_u32_e32 vcc, v3, v2
	s_and_saveexec_b64 s[4:5], vcc
	s_xor_b64 s[4:5], exec, s[4:5]
	s_cbranch_execz .LBB0_1184
	v_readlane_b32 s18, v252, 15
	v_readlane_b32 s19, v252, 16
	s_waitcnt lgkmcnt(0)
	s_nop 3
	global_load_dword v0, v64, s[18:19] sc1
	s_waitcnt vmcnt(0)
	v_cmp_eq_u32_e32 vcc, v0, v1
	s_and_saveexec_b64 s[36:37], vcc
	s_cbranch_execz .LBB0_1183
	s_mov_b32 s10, 1
	s_mov_b64 s[38:39], 0
	s_branch .LBB0_1174

.LBB0_1178:
	v_readlane_b32 s18, v252, 15
	v_readlane_b32 s19, v252, 16
	s_add_i32 s10, s10, 1
	s_mov_b64 s[44:45], -1
	s_nop 2
	global_load_dword v0, v64, s[18:19] sc1
	s_waitcnt vmcnt(0)
	v_cmp_ne_u32_e32 vcc, v0, v1
	s_orn2_b64 s[42:43], vcc, exec
	s_branch .LBB0_1173
